# dn_scan: next-chunk loads issued in the LDS-latency shadows of the MFMA chains via scalar base + 32-bit lane offset (no address block between barrier and first MFMA)
# baseline (speedup 1.0000x reference)
; DI unsigned char* launder_ptr(unsigned char* q) { asm volatile("" : "+s"(q)); return q; }
; DI int opaque_tid() { int t = threadIdx.x; asm volatile("" : "+v"(t)); return t; }
; DI f32x16 zero16() { f32x16 z; for (int i = 0; i < 16; ++i) z[i] = 0.f; return z; }
; DI void dn_scan_block(const Params& p, int chain_in, unsigned char* smem) {
;   int chain = blockIdx.x; asm volatile("" : "+v"(chain)); chain = __builtin_amdgcn_readfirstlane(chain) - chain_in;
;   unsigned char* const WS_ = launder_ptr(p.ws);
;   const int tid = opaque_tid(), lane = tid & 63, sl = tid >> 6, l31 = lane & 31, h = lane >> 5;
;   const int hd = chain & 3, b = (chain >> 2) & 3, dir = chain >> 4;
;   float* ODN = (float*)(WS_ + O_ODN) + (size_t)dir * NTOK * 512;
;   const float* GL = (const float*)(WS_ + O_DNG);
;   bfr* sU = (bfr*)smem;
;   const bfr *s_wneg = sU, *s_qdec = sU + 8192, *s_kdT = sU + 16384, *s_aqk = sU + 24576, *s_u = sU + 28672;
;   const u32x4* src = (const u32x4*)(WS_ + O_DNU) + (size_t)chain * 68 * 4608;
;   u32x4 st[18];
; #pragma unroll
;   for (int i = 0; i < 18; ++i) st[i] = src[tid + 256 * i];
;   f32x16 S[4];
;   for (int i = 0; i < 4; ++i) S[i] = zero16();
.LBB0_505:
	s_andn2_b64 vcc, exec, s[4:5]
	s_cbranch_vccnz .LBB0_510
	v_readlane_b32 s4, v254, 28
	s_mov_b32 s8, 0
	s_nop 5
	v_mov_b32_e32 v0, s4
	s_mov_b64 s[4:5], s[84:85]
	v_readfirstlane_b32 s21, v0
	s_ashr_i32 s6, s21, 4
	s_mul_hi_i32 s7, s6, 0x2200000
	s_mul_i32 s6, s6, 0x2200000
	s_add_u32 s22, s4, s6
	s_addc_u32 s23, s5, s7
	s_mul_i32 s6, s21, 0x4c8000
	v_mov_b32_e32 v0, v216
	s_mul_hi_i32 s7, s21, 0x4c8000
	s_add_u32 s6, s4, s6
	s_addc_u32 s7, s5, s7
	v_ashrrev_i32_e32 v1, 31, v0
	v_lshl_add_u64 v[212:213], v[0:1], 4, s[6:7]
	v_subrev_u32_e32 v241, s84, v212
	v_add_u32_e32 v241, 0x53cdf400, v241
	s_mov_b32 s6, 0x53ccd000
	v_add_co_u32_e32 v2, vcc, s6, v212
	s_mov_b32 s6, 0x53cce000
	s_nop 0
	v_addc_co_u32_e32 v3, vcc, 0, v213, vcc
	v_add_co_u32_e32 v4, vcc, s6, v212
	s_mov_b32 s6, 0x53ccf000
	s_nop 0
	v_addc_co_u32_e32 v5, vcc, 0, v213, vcc
	global_load_dwordx4 v[96:99], v[2:3], off offset:1024
	global_load_dwordx4 v[100:103], v[4:5], off offset:1024
	v_add_co_u32_e32 v2, vcc, s6, v212
	s_mov_b32 s6, 0x53cd0000
	s_nop 0
	v_addc_co_u32_e32 v3, vcc, 0, v213, vcc
	v_add_co_u32_e32 v4, vcc, s6, v212
	s_mov_b32 s6, 0x53cd1000
	s_nop 0
	v_addc_co_u32_e32 v5, vcc, 0, v213, vcc
	global_load_dwordx4 v[104:107], v[2:3], off offset:1024
	global_load_dwordx4 v[108:111], v[4:5], off offset:1024
	v_add_co_u32_e32 v2, vcc, s6, v212
	s_mov_b32 s6, 0x53cd2000
	s_nop 0
	v_addc_co_u32_e32 v3, vcc, 0, v213, vcc
	v_add_co_u32_e32 v4, vcc, s6, v212
	s_mov_b32 s6, 0x53cd3000
	s_nop 0
	v_addc_co_u32_e32 v5, vcc, 0, v213, vcc
	global_load_dwordx4 v[112:115], v[2:3], off offset:1024
	global_load_dwordx4 v[116:119], v[4:5], off offset:1024
	v_add_co_u32_e32 v2, vcc, s6, v212
	s_mov_b32 s6, 0x53cd4000
	s_nop 0
	v_addc_co_u32_e32 v3, vcc, 0, v213, vcc
	v_add_co_u32_e32 v4, vcc, s6, v212
	s_mov_b32 s6, 0x53cd5000
	s_nop 0
	v_addc_co_u32_e32 v5, vcc, 0, v213, vcc
	global_load_dwordx4 v[120:123], v[2:3], off offset:1024
	global_load_dwordx4 v[124:127], v[4:5], off offset:1024
	v_add_co_u32_e32 v2, vcc, s6, v212
	s_mov_b32 s6, 0x53cd6000
	s_nop 0
	v_addc_co_u32_e32 v3, vcc, 0, v213, vcc
	v_add_co_u32_e32 v4, vcc, s6, v212
	s_mov_b32 s6, 0x53cd7000
	s_nop 0
	v_addc_co_u32_e32 v5, vcc, 0, v213, vcc
	global_load_dwordx4 v[128:131], v[2:3], off offset:1024
	global_load_dwordx4 v[132:135], v[4:5], off offset:1024
	v_add_co_u32_e32 v2, vcc, s6, v212
	s_mov_b32 s6, 0x53cd8000
	s_nop 0
	v_addc_co_u32_e32 v3, vcc, 0, v213, vcc
	v_add_co_u32_e32 v4, vcc, s6, v212
	s_mov_b32 s6, 0x53cd9000
	s_nop 0
	v_addc_co_u32_e32 v5, vcc, 0, v213, vcc
	global_load_dwordx4 v[136:139], v[2:3], off offset:1024
	global_load_dwordx4 v[140:143], v[4:5], off offset:1024
	v_add_co_u32_e32 v2, vcc, s6, v212
	s_mov_b32 s6, 0x53cda000
	s_nop 0
	v_addc_co_u32_e32 v3, vcc, 0, v213, vcc
	v_add_co_u32_e32 v4, vcc, s6, v212
	s_mov_b32 s6, 0x53cdb000
	s_nop 0
	v_addc_co_u32_e32 v5, vcc, 0, v213, vcc
	global_load_dwordx4 v[144:147], v[2:3], off offset:1024
	global_load_dwordx4 v[148:151], v[4:5], off offset:1024
	v_add_co_u32_e32 v2, vcc, s6, v212
	s_mov_b32 s6, 0x53cdc000
	s_nop 0
	v_addc_co_u32_e32 v3, vcc, 0, v213, vcc
	v_add_co_u32_e32 v4, vcc, s6, v212
	s_mov_b32 s6, 0x53cdd000
	s_nop 0
	v_addc_co_u32_e32 v5, vcc, 0, v213, vcc
	global_load_dwordx4 v[152:155], v[2:3], off offset:1024
	global_load_dwordx4 v[156:159], v[4:5], off offset:1024
	v_add_co_u32_e32 v2, vcc, s6, v212
	s_mov_b32 s6, 0x53cde000
	s_nop 0
	v_addc_co_u32_e32 v3, vcc, 0, v213, vcc
	v_add_co_u32_e32 v4, vcc, s6, v212
	s_bfe_u32 s20, s21, 0x20002
	s_nop 0
	v_addc_co_u32_e32 v5, vcc, 0, v213, vcc
	global_load_dwordx4 v[160:163], v[2:3], off offset:1024
	global_load_dwordx4 v[164:167], v[4:5], off offset:1024
	s_add_u32 s9, s4, 0x5d5cd400
	s_addc_u32 s10, s5, 0
	s_cmp_lt_u32 s21, 16
	s_cselect_b64 s[4:5], -1, 0
	s_lshl_b32 s6, s21, 9
	v_ashrrev_i32_e32 v6, 6, v0
	v_and_b32_e32 v1, 63, v0
	v_and_b32_e32 v2, 31, v0
	v_lshlrev_b32_e32 v223, 4, v0
	v_lshrrev_b32_e32 v0, 3, v0
	s_and_b32 s6, s6, 0x600
	v_lshlrev_b32_e32 v3, 5, v1
	v_lshlrev_b32_e32 v1, 4, v1
	v_and_b32_e32 v225, 4, v0
	v_lshlrev_b32_e32 v0, 5, v6
	s_add_u32 s6, s22, s6
	v_sub_u32_e32 v224, v3, v1
	v_ashrrev_i32_e32 v1, 31, v0
	s_addc_u32 s7, s23, 0
	s_add_u32 s30, s6, 0x5d5cf600
	s_addc_u32 s31, s7, 0
	v_lshl_add_u64 v[0:1], v[0:1], 2, s[6:7]
	v_lshlrev_b32_e32 v208, 2, v2
	v_lshl_add_u64 v[0:1], v[0:1], 0, v[208:209]
	s_mov_b64 s[6:7], 0x5d5cf600
	v_lshl_add_u64 v[214:215], v[0:1], 0, s[6:7]
	v_lshrrev_b32_e32 v230, 6, v216
	v_and_b32_e32 v233, 31, v216
	v_lshlrev_b32_e32 v230, 7, v230
	v_lshlrev_b32_e32 v238, 11, v225
	v_lshl_or_b32 v230, v233, 2, v230
	v_sub_u32_e32 v233, 0xf800, v238
	v_mov_b32_e32 v232, 0x800
	v_cndmask_b32_e64 v238, v233, v238, s[4:5]
	v_mov_b32_e32 v233, 0xfffff800
	v_add_u32_e32 v230, v230, v238
	v_cndmask_b32_e64 v232, v233, v232, s[4:5]
	v_lshl_or_b32 v226, v6, 11, v3
	v_mov_b32_e32 v0, 0
	s_mul_i32 s11, s21, 0x44
	s_mulk_i32 s20, 0x1100
	v_add_u32_e32 v227, 0xe000, v226
	v_or_b32_e32 v228, 1, v225
	v_or_b32_e32 v229, 2, v225
	v_or_b32_e32 v231, 3, v225
	v_or_b32_e32 v235, 8, v225
	v_or_b32_e32 v236, 9, v225
	v_or_b32_e32 v245, 10, v225
	v_or_b32_e32 v246, 11, v225
	v_or_b32_e32 v247, 16, v225
	v_or_b32_e32 v248, 17, v225
	v_or_b32_e32 v249, 18, v225
	v_or_b32_e32 v250, 19, v225
	v_or_b32_e32 v251, 24, v225
	v_or_b32_e32 v252, 25, v225
	v_or_b32_e32 v253, 26, v225
	v_or_b32_e32 v237, 27, v225
	s_mov_b64 s[6:7], 0
	v_mov_b32_e32 v1, v0
	v_mov_b32_e32 v2, v0
	v_mov_b32_e32 v3, v0
	v_mov_b32_e32 v4, v0
	v_mov_b32_e32 v5, v0
	v_mov_b32_e32 v6, v0
	v_mov_b32_e32 v7, v0
	v_mov_b32_e32 v8, v0
	v_mov_b32_e32 v9, v0
	v_mov_b32_e32 v10, v0
	v_mov_b32_e32 v11, v0
	v_mov_b32_e32 v12, v0
	v_mov_b32_e32 v13, v0
	v_mov_b32_e32 v14, v0
	v_mov_b32_e32 v15, v0
	v_mov_b32_e32 v16, v0
	v_mov_b32_e32 v17, v0
	v_mov_b32_e32 v18, v0
	v_mov_b32_e32 v19, v0
	v_mov_b32_e32 v20, v0
	v_mov_b32_e32 v21, v0
	v_mov_b32_e32 v22, v0
	v_mov_b32_e32 v23, v0
	v_mov_b32_e32 v24, v0
	v_mov_b32_e32 v25, v0
	v_mov_b32_e32 v26, v0
	v_mov_b32_e32 v27, v0
	v_mov_b32_e32 v28, v0
	v_mov_b32_e32 v29, v0
	v_mov_b32_e32 v30, v0
	v_mov_b32_e32 v31, v0
	v_mov_b32_e32 v32, v0
	v_mov_b32_e32 v33, v0
	v_mov_b32_e32 v34, v0
	v_mov_b32_e32 v35, v0
	v_mov_b32_e32 v36, v0
	v_mov_b32_e32 v37, v0
	v_mov_b32_e32 v38, v0
	v_mov_b32_e32 v39, v0
	v_mov_b32_e32 v40, v0
	v_mov_b32_e32 v41, v0
	v_mov_b32_e32 v42, v0
	v_mov_b32_e32 v43, v0
	v_mov_b32_e32 v44, v0
	v_mov_b32_e32 v45, v0
	v_mov_b32_e32 v46, v0
	v_mov_b32_e32 v47, v0
	v_mov_b32_e32 v48, v0
	v_mov_b32_e32 v49, v0
	v_mov_b32_e32 v50, v0
	v_mov_b32_e32 v51, v0
	v_mov_b32_e32 v52, v0
	v_mov_b32_e32 v53, v0
	v_mov_b32_e32 v54, v0
	v_mov_b32_e32 v55, v0
	v_mov_b32_e32 v56, v0
	v_mov_b32_e32 v57, v0
	v_mov_b32_e32 v58, v0
	v_mov_b32_e32 v59, v0
	v_mov_b32_e32 v60, v0
	v_mov_b32_e32 v61, v0
	v_mov_b32_e32 v62, v0
	v_mov_b32_e32 v63, v0
	s_branch .LBB0_508
; #define MFMA(a, b, c) __builtin_amdgcn_mfma_f32_32x32x16_bf16((a), (b), (c), 0, 0, 0)
; DI void stream_of(int n, int cpc, int& m, int& T, int& soff) { if (n < cpc) { m = n; T = CTX; soff = 0; } else { m = n - cpc; T = SEQ; soff = CTX; } }
; DI void dn_scan_block(const Params& p, int chain_in, unsigned char* smem) {
;     ...
;     if (n + 1 < 68) {
; #pragma unroll
;       for (int i = 0; i < 18; ++i) st[i] = src[(size_t)(n + 1) * 4608 + tid + 256 * i];
;     }
;     const float gl = GL[chain * 68 + n];
;     int m, T, soff; stream_of(n, 4, m, T, soff);
;     f32x16 vn[2];
; #pragma unroll
;     for (int mb = 0; mb < 2; ++mb) {
;       unpack16(s_u + ((mb * 4 + sl) * 64 + lane) * 16, vn[mb]);
; #pragma unroll
;       for (int k = 0; k < 4; ++k) {
;         vn[mb] = MFMA(ld16(s_wneg + (((mb * 4 + k) * 2 + 0) * 64 + lane) * 8), pack8<0>(S[k]), vn[mb]);
;         vn[mb] = MFMA(ld16(s_wneg + (((mb * 4 + k) * 2 + 1) * 64 + lane) * 8), pack8<1>(S[k]), vn[mb]);
;       }
;     }
.LBB0_507:
	ds_read_b128 v[76:79], v226 offset:57344
	ds_read_b128 v[80:83], v226 offset:57360
	v_cvt_pk_bf16_f32 v176, v48, v49
	v_cvt_pk_bf16_f32 v177, v50, v51
	v_cvt_pk_bf16_f32 v178, v52, v53
	s_waitcnt lgkmcnt(0)
	v_and_b32_e32 v65, 0xffff0000, v76
	v_lshlrev_b32_e32 v64, 16, v76
	v_and_b32_e32 v73, 0xffff0000, v80
	v_lshlrev_b32_e32 v72, 16, v80
	v_and_b32_e32 v67, 0xffff0000, v77
	v_lshlrev_b32_e32 v66, 16, v77
	v_and_b32_e32 v75, 0xffff0000, v81
	v_lshlrev_b32_e32 v74, 16, v81
	v_and_b32_e32 v69, 0xffff0000, v78
	v_lshlrev_b32_e32 v68, 16, v78
	v_and_b32_e32 v77, 0xffff0000, v82
	v_lshlrev_b32_e32 v76, 16, v82
	v_and_b32_e32 v71, 0xffff0000, v79
	v_lshlrev_b32_e32 v70, 16, v79
	v_and_b32_e32 v79, 0xffff0000, v83
	v_lshlrev_b32_e32 v78, 16, v83
	ds_read_b128 v[80:83], v224
	v_cvt_pk_bf16_f32 v179, v54, v55
	v_cvt_pk_bf16_f32 v180, v56, v57
	v_cvt_pk_bf16_f32 v181, v58, v59
	s_waitcnt lgkmcnt(0)
	v_mfma_f32_32x32x16_bf16 v[64:79], v[80:83], v[176:179], v[64:79]
	ds_read_b128 v[80:83], v224 offset:1024
	v_cvt_pk_bf16_f32 v182, v60, v61
	v_cvt_pk_bf16_f32 v183, v62, v63
	v_cvt_pk_bf16_f32 v184, v32, v33
	v_cvt_pk_bf16_f32 v185, v34, v35
	v_cvt_pk_bf16_f32 v186, v36, v37
	v_cvt_pk_bf16_f32 v187, v38, v39
	s_waitcnt lgkmcnt(0)
	v_mfma_f32_32x32x16_bf16 v[64:79], v[80:83], v[180:183], v[64:79]
	ds_read_b128 v[80:83], v224 offset:2048
	v_cvt_pk_bf16_f32 v188, v40, v41
	v_cvt_pk_bf16_f32 v189, v42, v43
	v_cvt_pk_bf16_f32 v190, v44, v45
	v_cvt_pk_bf16_f32 v191, v46, v47
	v_cvt_pk_bf16_f32 v192, v16, v17
	v_cvt_pk_bf16_f32 v193, v18, v19
	s_waitcnt lgkmcnt(0)
	v_mfma_f32_32x32x16_bf16 v[64:79], v[80:83], v[184:187], v[64:79]
	ds_read_b128 v[80:83], v224 offset:3072
	v_cvt_pk_bf16_f32 v194, v20, v21
	v_cvt_pk_bf16_f32 v195, v22, v23
	v_cvt_pk_bf16_f32 v196, v24, v25
	v_cvt_pk_bf16_f32 v197, v26, v27
	v_cvt_pk_bf16_f32 v198, v28, v29
	v_cvt_pk_bf16_f32 v199, v30, v31
	s_waitcnt lgkmcnt(0)
	v_mfma_f32_32x32x16_bf16 v[64:79], v[80:83], v[188:191], v[64:79]
	ds_read_b128 v[80:83], v224 offset:4096
	v_cvt_pk_bf16_f32 v200, v0, v1
	v_cvt_pk_bf16_f32 v201, v2, v3
	v_cvt_pk_bf16_f32 v202, v4, v5
	v_cvt_pk_bf16_f32 v203, v6, v7
	v_cvt_pk_bf16_f32 v204, v8, v9
	v_cvt_pk_bf16_f32 v205, v10, v11
	s_waitcnt lgkmcnt(0)
	v_mfma_f32_32x32x16_bf16 v[64:79], v[80:83], v[192:195], v[64:79]
	ds_read_b128 v[80:83], v224 offset:5120
	v_cvt_pk_bf16_f32 v206, v12, v13
	v_cvt_pk_bf16_f32 v207, v14, v15
	s_cmp_lt_u32 s8, 4
	s_cselect_b32 s22, 0, -4
	s_cselect_b32 s21, 0x100, s95
	s_waitcnt lgkmcnt(0)
	v_mfma_f32_32x32x16_bf16 v[64:79], v[80:83], v[196:199], v[64:79]
	ds_read_b128 v[80:83], v224 offset:6144
	s_waitcnt lgkmcnt(0)
	v_mfma_f32_32x32x16_bf16 v[64:79], v[80:83], v[200:203], v[64:79]
	ds_read_b128 v[80:83], v224 offset:7168
	ds_read_b128 v[92:95], v227 offset:8192
	ds_read_b128 v[168:171], v227 offset:8208
	s_waitcnt lgkmcnt(0)
	v_and_b32_e32 v85, 0xffff0000, v94
	v_and_b32_e32 v89, 0xffff0000, v168
	v_mfma_f32_32x32x16_bf16 v[64:79], v[80:83], v[204:207], v[64:79]
	v_and_b32_e32 v81, 0xffff0000, v92
	v_lshlrev_b32_e32 v80, 16, v92
	v_lshlrev_b32_e32 v88, 16, v168
	v_and_b32_e32 v83, 0xffff0000, v93
	v_lshlrev_b32_e32 v82, 16, v93
	v_and_b32_e32 v91, 0xffff0000, v169
	v_lshlrev_b32_e32 v90, 16, v169
	v_lshlrev_b32_e32 v84, 16, v94
	v_and_b32_e32 v93, 0xffff0000, v170
	v_lshlrev_b32_e32 v92, 16, v170
	v_and_b32_e32 v87, 0xffff0000, v95
	v_lshlrev_b32_e32 v86, 16, v95
	v_and_b32_e32 v95, 0xffff0000, v171
	v_lshlrev_b32_e32 v94, 16, v171
	ds_read_b128 v[168:171], v224 offset:8192
	s_waitcnt vmcnt(0)
	global_load_dwordx4 v[96:99], v242, s[84:85]
	s_waitcnt lgkmcnt(0)
	v_mfma_f32_32x32x16_bf16 v[80:95], v[168:171], v[176:179], v[80:95]
	ds_read_b128 v[168:171], v224 offset:9216
	v_add_u32_e32 v238, 0x1000, v242
	global_load_dwordx4 v[100:103], v238, s[84:85]
	s_waitcnt lgkmcnt(0)
	v_mfma_f32_32x32x16_bf16 v[80:95], v[168:171], v[180:183], v[80:95]
	ds_read_b128 v[168:171], v224 offset:10240
	v_add_u32_e32 v239, 0x2000, v242
	global_load_dwordx4 v[104:107], v239, s[84:85]
	s_waitcnt lgkmcnt(0)
	v_mfma_f32_32x32x16_bf16 v[80:95], v[168:171], v[184:187], v[80:95]
	ds_read_b128 v[168:171], v224 offset:11264
	v_add_u32_e32 v240, 0x3000, v242
	global_load_dwordx4 v[108:111], v240, s[84:85]
	s_waitcnt lgkmcnt(0)
	v_mfma_f32_32x32x16_bf16 v[80:95], v[168:171], v[188:191], v[80:95]
	ds_read_b128 v[168:171], v224 offset:12288
	v_add_u32_e32 v233, 0x4000, v242
	global_load_dwordx4 v[112:115], v233, s[84:85]
	s_waitcnt lgkmcnt(0)
	v_mfma_f32_32x32x16_bf16 v[80:95], v[168:171], v[192:195], v[80:95]
	ds_read_b128 v[168:171], v224 offset:13312
	v_add_u32_e32 v238, 0x5000, v242
	global_load_dwordx4 v[116:119], v238, s[84:85]
	s_waitcnt lgkmcnt(0)
	v_mfma_f32_32x32x16_bf16 v[80:95], v[168:171], v[196:199], v[80:95]
	ds_read_b128 v[168:171], v224 offset:14336
	v_add_u32_e32 v239, 0x6000, v242
	global_load_dwordx4 v[120:123], v239, s[84:85]
	s_waitcnt lgkmcnt(0)
	v_mfma_f32_32x32x16_bf16 v[80:95], v[168:171], v[200:203], v[80:95]
	ds_read_b128 v[168:171], v224 offset:15360
	v_add_u32_e32 v240, 0x7000, v242
	global_load_dwordx4 v[124:127], v240, s[84:85]
	s_waitcnt lgkmcnt(0)
	v_mfma_f32_32x32x16_bf16 v[80:95], v[168:171], v[204:207], v[80:95]
	v_cvt_pk_bf16_f32 v172, v64, v65
	v_cvt_pk_bf16_f32 v173, v66, v67
	v_cvt_pk_bf16_f32 v174, v68, v69
	v_cvt_pk_bf16_f32 v175, v70, v71
	v_cvt_pk_bf16_f32 v168, v72, v73
	v_cvt_pk_bf16_f32 v169, v74, v75
	v_cvt_pk_bf16_f32 v170, v76, v77
	v_cvt_pk_bf16_f32 v171, v78, v79
	s_nop 3
	v_cvt_pk_bf16_f32 v80, v80, v81
	v_cvt_pk_bf16_f32 v81, v82, v83
	v_cvt_pk_bf16_f32 v82, v84, v85
	v_cvt_pk_bf16_f32 v83, v86, v87
	v_cvt_pk_bf16_f32 v84, v88, v89
	v_cvt_pk_bf16_f32 v85, v90, v91
	v_cvt_pk_bf16_f32 v86, v92, v93
	v_cvt_pk_bf16_f32 v87, v94, v95
	s_cselect_b32 s24, 0, 0x100
	s_add_i32 s22, s22, s8
	ds_read_b128 v[64:67], v224 offset:16384
	ds_read_b128 v[88:91], v224 offset:17408
	s_lshl_b32 s23, s22, 6
	s_add_i32 s22, s24, s20
	s_waitcnt lgkmcnt(0)
; #define MFMA(a, b, c) __builtin_amdgcn_mfma_f32_32x32x16_bf16((a), (b), (c), 0, 0, 0)
; DI int crow(int r, int h) { return (r & 3) + 8 * (r >> 2) + 4 * h; }
; DI f32x16 zero16() { f32x16 z; for (int i = 0; i < 16; ++i) z[i] = 0.f; return z; }
; DI void dn_scan_block(const Params& p, int chain_in, unsigned char* smem) {
;     ...
; #pragma unroll
;     for (int mb = 0; mb < 2; ++mb) {
;       f32x16 o = zero16();
; #pragma unroll
;       for (int k = 0; k < 4; ++k) {
;         o = MFMA(ld16(s_qdec + (((mb * 4 + k) * 2 + 0) * 64 + lane) * 8), pack8<0>(S[k]), o);
;         o = MFMA(ld16(s_qdec + (((mb * 4 + k) * 2 + 1) * 64 + lane) * 8), pack8<1>(S[k]), o);
;       }
; #pragma unroll
;       for (int jb = 0; jb < 2; ++jb)
; #pragma unroll
;         for (int s = 0; s < 2; ++s) o = MFMA(ld16(s_aqk + (((mb * 2 + jb) * 2 + s) * 64 + lane) * 8), vp[jb][s], o);
; #pragma unroll
;       for (int r = 0; r < 16; ++r) {
;         const int pos = 64 * m + 32 * mb + crow(r, h), t = dir ? T - 1 - pos : pos;
;         ODN[(size_t)(b * SP + soff + t) * 512 + hd * 128 + 32 * sl + l31] = o[r];
;       }
	v_mfma_f32_32x32x16_bf16 v[64:79], v[64:67], v[176:179], 0
	v_mfma_f32_32x32x16_bf16 v[64:79], v[88:91], v[180:183], v[64:79]
	ds_read_b128 v[88:91], v224 offset:18432
	v_add_u32_e32 v233, 0x8000, v242
	global_load_dwordx4 v[128:131], v233, s[84:85]
	s_waitcnt lgkmcnt(0)
	v_mfma_f32_32x32x16_bf16 v[64:79], v[88:91], v[184:187], v[64:79]
	ds_read_b128 v[88:91], v224 offset:19456
	v_add_u32_e32 v238, 0x9000, v242
	global_load_dwordx4 v[132:135], v238, s[84:85]
	s_waitcnt lgkmcnt(0)
	v_mfma_f32_32x32x16_bf16 v[64:79], v[88:91], v[188:191], v[64:79]
	ds_read_b128 v[88:91], v224 offset:20480
	v_add_u32_e32 v239, 0xa000, v242
	global_load_dwordx4 v[136:139], v239, s[84:85]
	s_waitcnt lgkmcnt(0)
	v_mfma_f32_32x32x16_bf16 v[64:79], v[88:91], v[192:195], v[64:79]
	ds_read_b128 v[88:91], v224 offset:21504
	v_add_u32_e32 v240, 0xb000, v242
	global_load_dwordx4 v[140:143], v240, s[84:85]
	s_waitcnt lgkmcnt(0)
	v_mfma_f32_32x32x16_bf16 v[64:79], v[88:91], v[196:199], v[64:79]
	ds_read_b128 v[88:91], v224 offset:22528
	v_add_u32_e32 v233, 0xc000, v242
	global_load_dwordx4 v[144:147], v233, s[84:85]
	s_waitcnt lgkmcnt(0)
	v_mfma_f32_32x32x16_bf16 v[64:79], v[88:91], v[200:203], v[64:79]
	ds_read_b128 v[88:91], v224 offset:23552
	v_add_u32_e32 v238, 0xd000, v242
	global_load_dwordx4 v[148:151], v238, s[84:85]
	s_waitcnt lgkmcnt(0)
	v_mfma_f32_32x32x16_bf16 v[64:79], v[88:91], v[204:207], v[64:79]
	ds_read_b128 v[88:91], v224 offset:49152
	v_add_u32_e32 v239, 0xe000, v242
	global_load_dwordx4 v[152:155], v239, s[84:85]
	s_waitcnt lgkmcnt(0)
	v_mfma_f32_32x32x16_bf16 v[64:79], v[88:91], v[172:175], v[64:79]
	ds_read_b128 v[88:91], v224 offset:50176
	v_add_u32_e32 v240, 0xf000, v242
	global_load_dwordx4 v[156:159], v240, s[84:85]
	s_waitcnt lgkmcnt(0)
	v_mfma_f32_32x32x16_bf16 v[64:79], v[88:91], v[168:171], v[64:79]
	ds_read_b128 v[88:91], v224 offset:51200
	v_add_u32_e32 v233, 0x10000, v242
	global_load_dwordx4 v[160:163], v233, s[84:85]
	s_waitcnt lgkmcnt(0)
	v_mfma_f32_32x32x16_bf16 v[64:79], v[88:91], v[80:83], v[64:79]
	ds_read_b128 v[88:91], v224 offset:52224
	v_add_u32_e32 v238, 0x11000, v242
	global_load_dwordx4 v[164:167], v238, s[84:85]
	s_waitcnt lgkmcnt(0)
	v_mfma_f32_32x32x16_bf16 v[64:79], v[88:91], v[84:87], v[64:79]
	s_add_i32 s26, s22, s23
	s_sub_i32 s27, s21, s23
	s_add_i32 s27, s27, s22
	s_sub_i32 s27, s27, 32
	s_cmp_lg_u64 s[4:5], 0
	s_cselect_b32 s26, s26, s27
	s_lshl_b32 s26, s26, 11
	s_add_u32 s34, s30, s26
	s_addc_u32 s35, s31, 0
	s_nop 3
	v_mad_i32_i24 v233, v232, 0, v230
	global_store_dword v233, v64, s[34:35]
	v_mad_i32_i24 v238, v232, 1, v230
	global_store_dword v238, v65, s[34:35]
	v_mad_i32_i24 v239, v232, 2, v230
	global_store_dword v239, v66, s[34:35]
	v_mad_i32_i24 v240, v232, 3, v230
	global_store_dword v240, v67, s[34:35]
	v_mad_i32_i24 v233, v232, 8, v230
	global_store_dword v233, v68, s[34:35]
	v_mad_i32_i24 v238, v232, 9, v230
	global_store_dword v238, v69, s[34:35]
	v_mad_i32_i24 v239, v232, 10, v230
	global_store_dword v239, v70, s[34:35]
	v_mad_i32_i24 v240, v232, 11, v230
	global_store_dword v240, v71, s[34:35]
	v_mad_i32_i24 v233, v232, 16, v230
	global_store_dword v233, v72, s[34:35]
	v_mad_i32_i24 v238, v232, 17, v230
	global_store_dword v238, v73, s[34:35]
	v_mad_i32_i24 v239, v232, 18, v230
	global_store_dword v239, v74, s[34:35]
	v_mad_i32_i24 v240, v232, 19, v230
	global_store_dword v240, v75, s[34:35]
	v_mad_i32_i24 v233, v232, 24, v230
	global_store_dword v233, v76, s[34:35]
	v_mad_i32_i24 v238, v232, 25, v230
	global_store_dword v238, v77, s[34:35]
	v_mad_i32_i24 v239, v232, 26, v230
	global_store_dword v239, v78, s[34:35]
	v_mad_i32_i24 v240, v232, 27, v230
	global_store_dword v240, v79, s[34:35]
	ds_read_b128 v[64:67], v224 offset:24576
	ds_read_b128 v[88:91], v224 offset:25600
	s_or_b32 s23, s23, 32
	s_waitcnt lgkmcnt(0)
	v_mfma_f32_32x32x16_bf16 v[64:79], v[64:67], v[176:179], 0
	v_mfma_f32_32x32x16_bf16 v[64:79], v[88:91], v[180:183], v[64:79]
	ds_read_b128 v[88:91], v224 offset:26624
	s_waitcnt lgkmcnt(0)
	v_mfma_f32_32x32x16_bf16 v[64:79], v[88:91], v[184:187], v[64:79]
	ds_read_b128 v[88:91], v224 offset:27648
	s_waitcnt lgkmcnt(0)
	v_mfma_f32_32x32x16_bf16 v[64:79], v[88:91], v[188:191], v[64:79]
	ds_read_b128 v[88:91], v224 offset:28672
	s_waitcnt lgkmcnt(0)
	v_mfma_f32_32x32x16_bf16 v[64:79], v[88:91], v[192:195], v[64:79]
	ds_read_b128 v[88:91], v224 offset:29696
	s_waitcnt lgkmcnt(0)
	v_mfma_f32_32x32x16_bf16 v[64:79], v[88:91], v[196:199], v[64:79]
	ds_read_b128 v[88:91], v224 offset:30720
	s_waitcnt lgkmcnt(0)
	v_mfma_f32_32x32x16_bf16 v[64:79], v[88:91], v[200:203], v[64:79]
	ds_read_b128 v[88:91], v224 offset:31744
	s_waitcnt lgkmcnt(0)
	v_mfma_f32_32x32x16_bf16 v[64:79], v[88:91], v[204:207], v[64:79]
	ds_read_b128 v[88:91], v224 offset:53248
	s_waitcnt lgkmcnt(0)
	v_mfma_f32_32x32x16_bf16 v[64:79], v[88:91], v[172:175], v[64:79]
	ds_read_b128 v[88:91], v224 offset:54272
	s_waitcnt lgkmcnt(0)
	v_mfma_f32_32x32x16_bf16 v[64:79], v[88:91], v[168:171], v[64:79]
	ds_read_b128 v[88:91], v224 offset:55296
	s_waitcnt lgkmcnt(0)
	v_mfma_f32_32x32x16_bf16 v[64:79], v[88:91], v[80:83], v[64:79]
	ds_read_b128 v[88:91], v224 offset:56320
	s_waitcnt lgkmcnt(0)
; #define MFMA(a, b, c) __builtin_amdgcn_mfma_f32_32x32x16_bf16((a), (b), (c), 0, 0, 0)
; DI int crow(int r, int h) { return (r & 3) + 8 * (r >> 2) + 4 * h; }
; DI void dn_scan_block(const Params& p, int chain_in, unsigned char* smem) {
;     ...
;   for (int n = 0; n < 68; ++n) {
;     __syncthreads();
; #pragma unroll
;     for (int i = 0; i < 18; ++i) ((u32x4*)sU)[tid + 256 * i] = st[i];
;     __syncthreads();
;     if (n + 1 < 68) {
; #pragma unroll
;       for (int i = 0; i < 18; ++i) st[i] = src[(size_t)(n + 1) * 4608 + tid + 256 * i];
;     }
;     ...
; #pragma unroll
;       for (int r = 0; r < 16; ++r) {
;         const int pos = 64 * m + 32 * mb + crow(r, h), t = dir ? T - 1 - pos : pos;
;         ODN[(size_t)(b * SP + soff + t) * 512 + hd * 128 + 32 * sl + l31] = o[r];
;       }
;       __builtin_amdgcn_sched_barrier(0);
;     }
; #pragma unroll
;     for (int k = 0; k < 4; ++k) {
; #pragma unroll
;       for (int r = 0; r < 16; ++r) S[k][r] *= gl;
; #pragma unroll
;       for (int jb = 0; jb < 2; ++jb)
; #pragma unroll
;         for (int s = 0; s < 2; ++s) S[k] = MFMA(ld16(s_kdT + (((k * 2 + jb) * 2 + s) * 64 + lane) * 8), vp[jb][s], S[k]);
;     }
;   }
	v_mfma_f32_32x32x16_bf16 v[64:79], v[88:91], v[84:87], v[64:79]
	s_add_i32 s26, s22, s23
	s_sub_i32 s27, s21, s23
	s_add_i32 s27, s27, s22
	s_sub_i32 s27, s27, 32
	s_cmp_lg_u64 s[4:5], 0
	s_cselect_b32 s26, s26, s27
	s_lshl_b32 s26, s26, 11
	s_add_u32 s34, s30, s26
	s_addc_u32 s35, s31, 0
	s_nop 3
	v_mad_i32_i24 v233, v232, 0, v230
	global_store_dword v233, v64, s[34:35]
	v_mad_i32_i24 v238, v232, 1, v230
	global_store_dword v238, v65, s[34:35]
	v_mad_i32_i24 v239, v232, 2, v230
	global_store_dword v239, v66, s[34:35]
	v_mad_i32_i24 v240, v232, 3, v230
	global_store_dword v240, v67, s[34:35]
	v_mad_i32_i24 v233, v232, 8, v230
	global_store_dword v233, v68, s[34:35]
	v_mad_i32_i24 v238, v232, 9, v230
	global_store_dword v238, v69, s[34:35]
	v_mad_i32_i24 v239, v232, 10, v230
	global_store_dword v239, v70, s[34:35]
	v_mad_i32_i24 v240, v232, 11, v230
	global_store_dword v240, v71, s[34:35]
	v_mad_i32_i24 v233, v232, 16, v230
	global_store_dword v233, v72, s[34:35]
	v_mad_i32_i24 v238, v232, 17, v230
	global_store_dword v238, v73, s[34:35]
	v_mad_i32_i24 v239, v232, 18, v230
	global_store_dword v239, v74, s[34:35]
	v_mad_i32_i24 v240, v232, 19, v230
	global_store_dword v240, v75, s[34:35]
	v_mad_i32_i24 v233, v232, 24, v230
	global_store_dword v233, v76, s[34:35]
	v_mad_i32_i24 v238, v232, 25, v230
	global_store_dword v238, v77, s[34:35]
	v_mad_i32_i24 v239, v232, 26, v230
	global_store_dword v239, v78, s[34:35]
	v_mad_i32_i24 v240, v232, 27, v230
	global_store_dword v240, v79, s[34:35]
	ds_read_b128 v[64:67], v224 offset:32768
	v_pk_mul_f32 v[62:63], v[62:63], v[208:209] op_sel_hi:[1,0]
	v_pk_mul_f32 v[60:61], v[60:61], v[208:209] op_sel_hi:[1,0]
	v_pk_mul_f32 v[58:59], v[58:59], v[208:209] op_sel_hi:[1,0]
	v_pk_mul_f32 v[56:57], v[56:57], v[208:209] op_sel_hi:[1,0]
	v_pk_mul_f32 v[54:55], v[54:55], v[208:209] op_sel_hi:[1,0]
	v_pk_mul_f32 v[52:53], v[52:53], v[208:209] op_sel_hi:[1,0]
	v_pk_mul_f32 v[50:51], v[50:51], v[208:209] op_sel_hi:[1,0]
	v_pk_mul_f32 v[48:49], v[48:49], v[208:209] op_sel_hi:[1,0]
	v_pk_mul_f32 v[46:47], v[46:47], v[208:209] op_sel_hi:[1,0]
	v_pk_mul_f32 v[44:45], v[44:45], v[208:209] op_sel_hi:[1,0]
	s_waitcnt lgkmcnt(0)
	v_mfma_f32_32x32x16_bf16 v[48:63], v[64:67], v[172:175], v[48:63]
	ds_read_b128 v[64:67], v224 offset:33792
	v_mul_f32_e64 v42, v42, v208
	v_mul_f32_e64 v43, v43, v208
	v_mul_f32_e64 v40, v40, v208
	v_mul_f32_e64 v41, v41, v208
	v_pk_mul_f32 v[38:39], v[38:39], v[208:209] op_sel_hi:[1,0]
	v_pk_mul_f32 v[36:37], v[36:37], v[208:209] op_sel_hi:[1,0]
	v_pk_mul_f32 v[34:35], v[34:35], v[208:209] op_sel_hi:[1,0]
	v_pk_mul_f32 v[32:33], v[32:33], v[208:209] op_sel_hi:[1,0]
	s_waitcnt lgkmcnt(0)
	v_mfma_f32_32x32x16_bf16 v[48:63], v[64:67], v[168:171], v[48:63]
	ds_read_b128 v[64:67], v224 offset:34816
	v_mul_f32_e64 v30, v30, v208
	v_mul_f32_e64 v31, v31, v208
	v_mul_f32_e64 v28, v28, v208
	v_mul_f32_e64 v29, v29, v208
	v_pk_mul_f32 v[26:27], v[26:27], v[208:209] op_sel_hi:[1,0]
	v_pk_mul_f32 v[24:25], v[24:25], v[208:209] op_sel_hi:[1,0]
	v_pk_mul_f32 v[22:23], v[22:23], v[208:209] op_sel_hi:[1,0]
	v_pk_mul_f32 v[20:21], v[20:21], v[208:209] op_sel_hi:[1,0]
	s_waitcnt lgkmcnt(0)
	v_mfma_f32_32x32x16_bf16 v[48:63], v[64:67], v[80:83], v[48:63]
	ds_read_b128 v[64:67], v224 offset:35840
	v_mul_f32_e64 v18, v18, v208
	v_mul_f32_e64 v19, v19, v208
	v_mul_f32_e64 v16, v16, v208
	v_mul_f32_e64 v17, v17, v208
	v_pk_mul_f32 v[14:15], v[14:15], v[208:209] op_sel_hi:[1,0]
	v_pk_mul_f32 v[12:13], v[12:13], v[208:209] op_sel_hi:[1,0]
	v_pk_mul_f32 v[10:11], v[10:11], v[208:209] op_sel_hi:[1,0]
	v_pk_mul_f32 v[8:9], v[8:9], v[208:209] op_sel_hi:[1,0]
	s_waitcnt lgkmcnt(0)
	v_mfma_f32_32x32x16_bf16 v[48:63], v[64:67], v[84:87], v[48:63]
	ds_read_b128 v[64:67], v224 offset:36864
	v_mul_f32_e64 v6, v6, v208
	v_mul_f32_e64 v7, v7, v208
	v_mul_f32_e64 v4, v4, v208
	v_mul_f32_e64 v5, v5, v208
	v_pk_mul_f32 v[2:3], v[2:3], v[208:209] op_sel_hi:[1,0]
	v_pk_mul_f32 v[0:1], v[0:1], v[208:209] op_sel_hi:[1,0]
	s_add_u32 s6, s6, 0x12000
	s_addc_u32 s7, s7, 0
	s_waitcnt lgkmcnt(0)
	v_mfma_f32_32x32x16_bf16 v[32:47], v[64:67], v[172:175], v[32:47]
	ds_read_b128 v[64:67], v224 offset:37888
	s_add_i32 s8, s8, 1
	s_cmp_eq_u32 s6, 0x4c8000
	s_waitcnt lgkmcnt(0)
	v_mfma_f32_32x32x16_bf16 v[32:47], v[64:67], v[168:171], v[32:47]
	ds_read_b128 v[64:67], v224 offset:38912
	s_waitcnt lgkmcnt(0)
	v_mfma_f32_32x32x16_bf16 v[32:47], v[64:67], v[80:83], v[32:47]
	ds_read_b128 v[64:67], v224 offset:39936
	s_waitcnt lgkmcnt(0)
	v_mfma_f32_32x32x16_bf16 v[32:47], v[64:67], v[84:87], v[32:47]
	ds_read_b128 v[64:67], v224 offset:40960
	s_waitcnt lgkmcnt(0)
	v_mfma_f32_32x32x16_bf16 v[16:31], v[64:67], v[172:175], v[16:31]
	ds_read_b128 v[64:67], v224 offset:41984
	s_waitcnt lgkmcnt(0)
	v_mfma_f32_32x32x16_bf16 v[16:31], v[64:67], v[168:171], v[16:31]
	ds_read_b128 v[64:67], v224 offset:43008
	s_waitcnt lgkmcnt(0)
	v_mfma_f32_32x32x16_bf16 v[16:31], v[64:67], v[80:83], v[16:31]
	ds_read_b128 v[64:67], v224 offset:44032
	s_waitcnt lgkmcnt(0)
	v_mfma_f32_32x32x16_bf16 v[16:31], v[64:67], v[84:87], v[16:31]
	ds_read_b128 v[64:67], v224 offset:45056
	s_waitcnt lgkmcnt(0)
	v_mfma_f32_32x32x16_bf16 v[0:15], v[64:67], v[172:175], v[0:15]
	ds_read_b128 v[64:67], v224 offset:46080
	s_waitcnt lgkmcnt(0)
	v_mfma_f32_32x32x16_bf16 v[0:15], v[64:67], v[168:171], v[0:15]
	ds_read_b128 v[64:67], v224 offset:47104
	s_waitcnt lgkmcnt(0)
	v_mfma_f32_32x32x16_bf16 v[0:15], v[64:67], v[80:83], v[0:15]
	ds_read_b128 v[64:67], v224 offset:48128
	s_waitcnt lgkmcnt(0)
	v_mfma_f32_32x32x16_bf16 v[0:15], v[64:67], v[84:87], v[0:15]
	s_waitcnt vmcnt(0)
	s_cbranch_scc1 .LBB0_510
.LBB0_508:
	v_add_u32_e32 v64, 0x10000, v223
	s_waitcnt lgkmcnt(0)
	s_barrier
	s_waitcnt vmcnt(0)
	s_add_i32 s22, s11, s8
	s_ashr_i32 s23, s22, 31
	s_lshl_b64 s[22:23], s[22:23], 2
	s_add_u32 s22, s9, s22
	s_addc_u32 s23, s10, s23
	s_nop 0
	global_load_dword v208, v209, s[22:23]
	ds_write_b128 v223, v[96:99]
	ds_write_b128 v223, v[100:103] offset:4096
	ds_write_b128 v223, v[104:107] offset:8192
	ds_write_b128 v223, v[108:111] offset:12288
	ds_write_b128 v223, v[112:115] offset:16384
	ds_write_b128 v223, v[116:119] offset:20480
	ds_write_b128 v223, v[120:123] offset:24576
	ds_write_b128 v223, v[124:127] offset:28672
	ds_write_b128 v223, v[128:131] offset:32768
	ds_write_b128 v223, v[132:135] offset:36864
	ds_write_b128 v223, v[136:139] offset:40960
	ds_write_b128 v223, v[140:143] offset:45056
	ds_write_b128 v223, v[144:147] offset:49152
	ds_write_b128 v223, v[148:151] offset:53248
	ds_write_b128 v223, v[152:155] offset:57344
	ds_write_b128 v223, v[156:159] offset:61440
	ds_write_b128 v64, v[160:163]
	v_add_u32_e32 v64, 0x11000, v223
	s_cmp_eq_u32 s6, 0x4b6000
	ds_write_b128 v64, v[164:167]
	s_waitcnt lgkmcnt(0)
	s_barrier
	s_cselect_b32 s28, 0, s6
	v_add_u32_e32 v242, s28, v241
	s_branch .LBB0_507
